# P3 rebalance: the 8 KV GEMM units that rode on DFT workgroups 100-107 now run on rmsnorm-group workgroups 188-195 (same units, static remap)
# speedup vs baseline: 1.0069x; 1.0069x over previous
; DI int opq0() { int z = 0; asm volatile("" : "+s"(z)); return z; }
; #define PH(k) if constexpr (((PHM) >> (k)) & 1u)
; __global__ void __launch_bounds__(512, 2) mega(Params P) {
;     ...
;             PH(4) { const int z = opq0(); Gemm g{WSP(bf16_t, WS_CQ), WGT(W_QB), 384, 384, 384, 0, 0}; S.init(MC / 256, 6, 1, 148, blk - 108, 0); if (blk < 108) { S.nwg = 0; S.c = 0; }
;               EpiQ E{WSP(bf16_t, WS_Q), WSP(const float2, WS_ROPE)}; pg8::gemm_phase(lds, g, S, E); }
;             PH(5) { const int z = opq0(); Gemm g{WSP(bf16_t, WS_CKV), WGT(W_KV), 256, 256, 256, 0, 0}; if (blk < 100) { S.init(1, 1, 1, 1, 0, 0); S.nwg = 0; } else if (blk < 108) { S.init(MC / 256, 8, 1, 8, blk - 100, 0); S.nwg = 8; } else { S.init(MC / 256, 8, 1, 148, blk - 108, 88); S.base = 8; }
_Z4mega6Params:
	v_writelane_b32 v255, s2, 9
	s_mov_b64 s[66:67], s[0:1]
	s_sub_i32 s0, s2, 40
	s_lshr_b32 s1, s0, 2
	s_mul_hi_u32 s1, s1, 0x1bacf915
	s_lshr_b32 s1, s1, 2
	s_mulk_i32 s1, 0x94
	s_sub_i32 s0, s0, s1
	s_cmpk_lt_i32 s2, 0x6c
	s_cselect_b32 s10, 0, 0
	s_add_i32 s1, s2, 0xffffff9c
	s_mov_b32 s70, s2
	s_cmpk_lt_i32 s2, 0x6c
	s_cselect_b32 s12, 0, 0x200
	s_cselect_b32 s2, 8, 0x94
	s_cselect_b32 s14, s1, s0
	s_add_i32 s0, s70, 40
	s_mul_hi_i32 s1, s0, 0xdd67c8a7
	v_writelane_b32 v253, s2, 0
	s_add_i32 s1, s1, s0
	s_load_dword s58, s[66:67], 0xd8
	s_load_dwordx4 s[20:23], s[66:67], 0xc8
	v_writelane_b32 v253, s3, 1
	s_lshr_b32 s2, s1, 31
	s_ashr_i32 s1, s1, 7
	s_add_i32 s1, s1, s2
	s_mulk_i32 s1, 0x94
	s_sub_i32 s0, s0, s1
	s_cmpk_lt_i32 s70, 0x6c
	s_cselect_b32 s74, 0, 0x180
	s_cselect_b32 s80, 0, s0
	s_add_u32 s0, s66, 0xd8
	s_addc_u32 s1, s67, 0
	s_waitcnt lgkmcnt(0)
	s_ashr_i32 s59, s58, 31
	v_writelane_b32 v253, s0, 2
	s_cmp_lg_u64 s[58:59], 0x100
	s_cselect_b64 s[82:83], -1, 0
	v_writelane_b32 v253, s1, 3
	s_lshl_b32 s0, s70, 9
	v_writelane_b32 v253, s0, 4
	s_lshl_b32 s84, s58, 9
	s_lshl_b32 s16, s70, 3
	s_lshl_b32 s34, s58, 3
	s_lshl_b32 s0, s70, 6
	s_add_i32 s2, s58, s70
	s_cmpk_gt_i32 s70, 0x63
	v_writelane_b32 v253, s0, 5
	s_cselect_b64 s[0:1], -1, 0
	v_writelane_b32 v253, s0, 6
	s_cmpk_gt_u32 s70, 0x9b
	s_mov_b32 s94, 0
	v_writelane_b32 v253, s1, 7
	s_cselect_b64 s[0:1], -1, 0
	v_writelane_b32 v253, s0, 8
	s_ashr_i32 s81, s80, 31
	s_add_i32 s6, s70, 0xc0
	v_writelane_b32 v253, s1, 9
	s_add_i32 s0, s16, 0xfffffb20
	v_writelane_b32 v253, s0, 10
	s_bfe_u32 s0, s80, 0x3001c
	s_add_i32 s0, s80, s0
	s_sext_i32_i16 s1, s0
	s_and_b32 s0, s0, 0xfff8
	s_sub_i32 s4, s80, s0
	s_lshl_b32 s0, s70, 2
	s_ashr_i32 s3, s1, 3
	s_and_b32 s0, s0, 28
	s_ashr_i32 s1, s70, 6
	s_add_i32 s7, s0, s1
	s_add_i32 s0, s70, 64
	s_mul_hi_i32 s1, s0, 0x66666667
	s_lshr_b32 s8, s1, 31
	s_ashr_i32 s1, s1, 6
	s_add_i32 s1, s1, s8
	s_mulk_i32 s1, 0xa0
	s_bfe_u32 s71, s70, 0x30003
	s_sub_i32 s8, s0, s1
	s_cmpk_lt_i32 s70, 0x60
	s_cselect_b64 s[0:1], -1, 0
	v_writelane_b32 v253, s0, 11
	s_sext_i32_i16 s5, s4
	s_mov_b32 s11, s94
	v_writelane_b32 v253, s1, 12
	s_and_b64 s[0:1], s[0:1], exec
	s_cselect_b32 s18, 0, s8
	s_cselect_b32 s24, 0, 0xc0
	s_bfe_u32 s0, s18, 0x3001c
	s_add_i32 s0, s18, s0
	s_sext_i32_i16 s1, s0
	s_and_b32 s0, s0, 0xfff8
	s_ashr_i32 s19, s18, 31
	s_ashr_i32 s1, s1, 3
	s_sub_i32 s0, s18, s0
	s_cmp_lt_i32 s5, 0
	s_cselect_b32 s8, 49, 48
	s_mul_i32 s4, s8, s4
	s_add_i32 s4, s4, s3
	s_sext_i32_i16 s3, s4
	s_mulk_i32 s3, 0x2aab
	s_lshr_b32 s8, s3, 31
	s_ashr_i32 s3, s3, 19
	s_add_i32 s3, s3, s8
	s_mul_i32 s8, s3, 48
	s_sub_i32 s4, s4, s8
	s_bfe_i32 s8, s4, 0x80000
	s_bfe_u32 s8, s8, 0x3000c
	s_add_i32 s8, s4, s8
	s_bfe_i32 s9, s8, 0x80000
	s_and_b32 s8, s8, 0xf8
	s_sub_i32 s4, s4, s8
	s_lshl_b32 s3, s3, 3
	s_sext_i32_i16 s9, s9
	s_sext_i32_i8 s4, s4
	s_add_i32 s72, s3, s4
	s_ashr_i32 s3, s9, 3
	v_writelane_b32 v253, s3, 13
	s_ashr_i32 s15, s14, 31
	s_sext_i32_i16 s5, s0
	v_writelane_b32 v253, s14, 14
	s_lshl_b32 s3, s7, 3
	s_cmp_lt_i32 s5, 0
	v_writelane_b32 v253, s15, 15
	v_writelane_b32 v253, s3, 16
	s_cselect_b32 s3, 25, 24
	s_mul_i32 s0, s3, s0
	s_add_i32 s0, s0, s1
	s_abs_i32 s5, s58
	s_sext_i32_i16 s1, s0
	v_cvt_f32_u32_e32 v1, s5
	s_mulk_i32 s1, 0x2aab
	s_lshr_b32 s3, s1, 31
	s_ashr_i32 s1, s1, 18
	s_add_i32 s1, s1, s3
	s_lshl_b32 s3, s1, 3
	s_mul_i32 s1, s1, 24
	v_rcp_iflag_f32_e32 v1, v1
	s_sub_i32 s0, s0, s1
	s_bfe_i32 s1, s0, 0x80000
	s_bfe_u32 s1, s1, 0x3000c
	s_add_i32 s1, s0, s1
	v_mul_f32_e32 v1, 0x4f7ffffe, v1
	s_bfe_i32 s4, s1, 0x80000
	s_and_b32 s1, s1, 0xf8
	v_cvt_u32_f32_e32 v1, v1
	s_sub_i32 s0, s0, s1
	s_sext_i32_i8 s0, s0
	s_sext_i32_i16 s4, s4
	s_add_i32 s0, s3, s0
	v_writelane_b32 v253, s0, 17
	s_ashr_i32 s0, s4, 3
	s_sub_i32 s3, 0, s5
	v_readfirstlane_b32 s4, v1
	s_mul_i32 s3, s3, s4
	s_mul_hi_u32 s3, s4, s3
	s_abs_i32 s1, s2
	s_add_i32 s3, s4, s3
	s_mul_hi_u32 s4, s1, s3
	s_mul_i32 s4, s4, s5
	s_sub_i32 s1, s1, s4
	v_writelane_b32 v253, s0, 18
	s_ashr_i32 s0, s2, 31
	s_sub_i32 s4, s1, s5
	s_cmp_ge_u32 s1, s5
	s_cselect_b32 s1, s4, s1
	s_sub_i32 s4, s1, s5
	s_cmp_ge_u32 s1, s5
	s_cselect_b32 s1, s4, s1
	s_xor_b32 s1, s1, s0
	s_sub_i32 s33, s1, s0
	s_ashr_i32 s4, s33, 31
	s_cmpk_lt_i32 s33, 0x480
	s_cselect_b64 s[0:1], -1, 0
	v_writelane_b32 v253, s0, 19
	v_and_b32_e32 v4, 0x3fffffff, v0
	v_writelane_b32 v254, s10, 0
	v_writelane_b32 v253, s1, 20
	s_mul_hi_i32 s0, s33, 0x38e38e39
	s_lshr_b32 s1, s0, 31
	s_lshr_b32 s0, s0, 8
	s_add_i32 s0, s0, s1
	s_mulk_i32 s0, 0x480
	s_sub_i32 s0, s33, s0
	s_sext_i32_i16 s1, s0
	s_bfe_u32 s1, s1, 0x3001c
	s_add_i32 s1, s0, s1
	s_sext_i32_i16 s7, s1
	s_and_b32 s1, s1, 0xfff8
	s_sub_i32 s0, s0, s1
	s_ashr_i32 s7, s7, 3
	s_sext_i32_i16 s1, s0
	s_cmp_lt_i32 s1, 0
	s_movk_i32 s1, 0x91
	s_cselect_b32 s1, s1, 0x90
	s_mul_i32 s0, s0, s1
	s_add_i32 s0, s0, s7
	s_sext_i32_i16 s1, s0
	s_mulk_i32 s1, 0xe39
	s_lshr_b32 s7, s1, 31
	s_ashr_i32 s1, s1, 19
	s_add_i32 s1, s1, s7
	s_lshl_b32 s7, s1, 3
	s_mulk_i32 s1, 0x90
	s_sub_i32 s0, s0, s1
	s_sext_i32_i16 s1, s0
	s_bfe_u32 s1, s1, 0x3001c
	s_add_i32 s1, s0, s1
	s_sext_i32_i16 s8, s1
	s_and_b32 s1, s1, 0xfff8
	s_sub_i32 s0, s0, s1
	s_sext_i32_i16 s0, s0
	s_add_i32 s0, s7, s0
	v_writelane_b32 v253, s0, 21
	s_ashr_i32 s0, s8, 3
	v_writelane_b32 v253, s0, 22
	s_cmpk_lt_i32 s33, 0x6c
	v_writelane_b32 v254, s11, 1
	v_writelane_b32 v253, s1, 23
	s_cselect_b64 s[0:1], -1, 0
	v_writelane_b32 v253, s0, 24
	s_mov_b32 s75, s94
	v_mov_b64_e32 v[2:3], s[80:81]
	v_writelane_b32 v253, s1, 25
	s_mul_hi_i32 s0, s33, 0x4bda12f7
	s_lshr_b32 s1, s0, 31
	s_lshr_b32 s0, s0, 5
;     DI bool next(int i, Unit& u) const {
;         const long L = (long)base + (long)i * G + c; if (L >= nwg) return false;
;         const int z = (int)(L / per); int wgid = (int)(L % per);
;         if (per >= 64) { const int q = per / NXCD, r = per % NXCD, xcd = wgid % NXCD, off = wgid / NXCD; wgid = (xcd < r ? xcd * (q + 1) : r * (q + 1) + (xcd - r) * q) + off; }
;         const int nig = WGM * nN, gid = wgid / nig, fm = gid * WGM, gsz = (nM - fm) < WGM ? (nM - fm) : WGM;
;         u.pm = fm + ((wgid % nig) % gsz); u.pn = (wgid % nig) / gsz; u.z = z; return true;
	s_add_i32 s0, s0, s1
	s_mulk_i32 s0, 0x6c
	s_sub_i32 s0, s33, s0
	s_bfe_i32 s1, s0, 0x80000
	s_bfe_u32 s1, s1, 0x3000c
	s_add_i32 s1, s0, s1
	s_bfe_i32 s7, s1, 0x80000
	s_sext_i32_i16 s7, s7
	s_lshr_b32 s7, s7, 3
	s_and_b32 s1, s1, 0xfff8
	v_writelane_b32 v253, s7, 26
	s_sub_i32 s7, s0, s1
	s_bfe_i32 s0, s7, 0x80000
	s_sext_i32_i16 s0, s0
	s_cmp_gt_i32 s0, 3
	s_cselect_b64 s[0:1], -1, 0
	v_writelane_b32 v253, s0, 27
	s_mov_b32 s25, s94
	v_and_b32_e32 v232, 0x3ff, v0
	v_writelane_b32 v253, s1, 28
	s_mul_i32 s0, s7, 13
	s_add_i32 s0, s0, 4
	v_writelane_b32 v253, s0, 29
	s_mul_hi_u32 s0, s3, 0x6c
	s_mul_i32 s0, s0, s5
	s_sub_i32 s0, 0x6c, s0
	s_sub_i32 s1, s0, s5
	s_cmp_ge_u32 s0, s5
	s_cselect_b32 s0, s1, s0
	s_sub_i32 s1, s0, s5
	s_cmp_ge_u32 s0, s5
	s_cselect_b32 s0, s1, s0
	s_sub_i32 s0, s2, s0
	s_ashr_i32 s1, s0, 31
	s_abs_i32 s0, s0
	s_mul_hi_u32 s2, s0, s3
	s_mul_i32 s2, s2, s5
	s_sub_i32 s0, s0, s2
	s_sub_i32 s2, s0, s5
	s_cmp_ge_u32 s0, s5
	s_cselect_b32 s0, s2, s0
	s_sub_i32 s2, s0, s5
	s_cmp_ge_u32 s0, s5
	s_cselect_b32 s0, s2, s0
	s_xor_b32 s0, s0, s1
	s_sub_i32 s1, s0, s1
	s_ashr_i32 s0, s1, 31
	s_cmp_lt_i32 s1, 48
	v_writelane_b32 v253, s0, 30
	s_cselect_b64 s[8:9], -1, 0
	s_lshr_b32 s0, s1, 31
	v_writelane_b32 v253, s8, 31
	s_add_i32 s0, s1, s0
	s_mov_b32 s13, s94
	v_writelane_b32 v253, s9, 32
	s_ashr_i32 s8, s0, 1
	s_and_b32 s0, s0, -2
	s_sub_i32 s2, s1, s0
	v_writelane_b32 v253, s1, 33
	s_mov_b32 s0, s2
	v_writelane_b32 v253, s0, 34
	s_ashr_i32 s9, s8, 31
	v_mbcnt_lo_u32_b32 v5, -1, 0
	v_writelane_b32 v253, s1, 35
	s_bfe_i64 s[0:1], s[2:3], 0x80000
	s_mul_hi_i32 s1, s0, 0x60000
	v_writelane_b32 v253, s1, 36
	s_mul_i32 s0, s0, 0x60000
	v_writelane_b32 v253, s0, 37
	s_abs_i32 s0, s6
	s_mov_b32 s2, s8
	s_mul_hi_u32 s1, s0, s3
	v_writelane_b32 v253, s2, 38
	s_mul_i32 s1, s1, s5
	s_sub_i32 s0, s0, s1
	v_writelane_b32 v253, s3, 39
	s_lshl_b64 s[2:3], s[8:9], 18
	v_writelane_b32 v253, s2, 40
	s_ashr_i32 s1, s6, 31
	v_mov_b32_e32 v189, 0
	v_writelane_b32 v253, s3, 41
	s_sub_i32 s2, s0, s5
	s_cmp_ge_u32 s0, s5
	s_cselect_b32 s0, s2, s0
	s_sub_i32 s2, s0, s5
	s_cmp_ge_u32 s0, s5
	s_cselect_b32 s0, s2, s0
	s_xor_b32 s0, s0, s1
	s_sub_i32 s0, s0, s1
	s_cmpk_lt_i32 s0, 0xc0
	s_cselect_b64 s[2:3], -1, 0
	v_writelane_b32 v253, s2, 42
	s_lshl_b32 s0, s0, 9
	s_cmpk_lt_i32 s33, 0x100
	v_writelane_b32 v253, s3, 43
	v_writelane_b32 v253, s0, 44
	s_cselect_b64 s[0:1], -1, 0
	v_writelane_b32 v253, s0, 45
	v_mov_b32_e32 v251, 0x1e000000
	v_mbcnt_hi_u32_b32 v233, -1, v5
	v_writelane_b32 v253, s1, 46
	s_lshr_b32 s0, s4, 24
	s_add_i32 s0, s33, s0
	s_and_b32 s0, s0, 0xff00
	s_sub_i32 s0, s33, s0
	s_sext_i32_i16 s1, s0
	s_bfe_u32 s1, s1, 0x3001c
	s_add_i32 s1, s0, s1
	s_and_b32 s2, s1, 0xfff8
	s_sub_i32 s2, s0, s2
	s_sext_i32_i16 s0, s1
	s_lshr_b32 s0, s0, 3
	v_writelane_b32 v253, s0, 47
	s_sext_i32_i16 s0, s2
	s_cmp_gt_i32 s0, -1
	s_cselect_b64 s[0:1], -1, 0
	v_writelane_b32 v253, s0, 48
	v_mov_b32_e32 v252, 0xfffffe80
	v_mov_b32_e32 v250, 0x700
	v_writelane_b32 v253, s1, 49
	s_lshl_b32 s0, s2, 5
	s_cmpk_lt_i32 s33, 0x60
	v_writelane_b32 v253, s0, 50
	s_cselect_b64 s[0:1], -1, 0
	v_writelane_b32 v253, s0, 51
	v_mov_b32_e32 v238, 1
	v_mov_b64_e32 v[190:191], 0x480
	v_writelane_b32 v253, s1, 52
	s_lshr_b32 s0, s4, 30
	s_add_i32 s3, s33, s0
	s_and_b32 s0, s3, 0xfffc
	s_sub_i32 s0, s33, s0
	s_bfe_u32 s1, s0, 0x10007
	s_add_i32 s5, s0, s1
	s_and_b32 s1, s5, 0xfffe
	s_sub_i32 s0, s0, s1
	s_sext_i32_i8 s1, s0
	v_writelane_b32 v253, s1, 53
	s_bfe_i64 s[0:1], s[0:1], 0x80000
	s_mul_hi_i32 s1, s0, 0x60000
	v_writelane_b32 v253, s1, 54
	s_mul_i32 s0, s0, 0x60000
	v_writelane_b32 v253, s0, 55
	s_bfe_i32 s0, s5, 0x80000
	s_sext_i32_i16 s0, s0
	s_ashr_i32 s6, s3, 2
	s_ashr_i32 s0, s0, 1
	s_cmpk_lt_i32 s33, 0x400
	v_writelane_b32 v253, s0, 56
	s_cselect_b64 s[0:1], -1, 0
; #define LAS __attribute__((address_space(3)))
; DI int opq0() { int z = 0; asm volatile("" : "+s"(z)); return z; }
; __global__ void __launch_bounds__(512, 2) mega(Params P) {
;     extern __shared__ __attribute__((aligned(16))) unsigned char smem_raw[];
;     LAS unsigned char* lds = (LAS unsigned char*)smem_raw;
;     cg::grid_group grid = cg::this_grid();
;     const int G = gridDim.x, blk = blockIdx.x;
;     Sched S;
;     ...
;     for (int layer = 0; layer < DEPTH; ++layer) {
;         { TID_VARS; if (layer == 0 && tid == 0) *(volatile LAS unsigned*)(lds + 131072) = 0u; if (layer == 0 && blk == 0) { unsigned* bw = (unsigned*)(P.ws + opq0() + WS_BAR); for (int i = tid; i < 4096; i += 512) bw[i] = 0u; } phase_prep(P, layer, blk * 512 + tid, G * 512); }
	v_writelane_b32 v253, s0, 57
	v_mov_b64_e32 v[192:193], 0x47f
	v_mov_b64_e32 v[194:195], 0x6c
	v_writelane_b32 v253, s1, 58
	s_lshr_b32 s0, s4, 22
	s_add_i32 s0, s33, s0
	s_and_b32 s0, s0, 0xfc00
	s_sub_i32 s0, s33, s0
	s_sext_i32_i16 s1, s0
	s_bfe_u32 s1, s1, 0x3001c
	s_add_i32 s1, s0, s1
	s_and_b32 s3, s1, 0xfff8
	s_sext_i32_i16 s1, s1
	s_sub_i32 s0, s0, s3
	s_lshr_b32 s1, s1, 3
	v_writelane_b32 v253, s1, 59
	s_sext_i32_i16 s1, s0
	s_cmp_gt_i32 s1, -1
	s_mul_i32 s1, s7, 14
	v_writelane_b32 v254, s1, 2
	s_mul_i32 s1, s2, 33
	v_writelane_b32 v254, s1, 3
	s_cselect_b64 s[2:3], -1, 0
	v_writelane_b32 v254, s2, 4
	s_lshl_b32 s1, s0, 7
	s_mulk_i32 s0, 0x81
	v_writelane_b32 v254, s3, 5
	v_writelane_b32 v254, s1, 6
	v_writelane_b32 v254, s0, 7
	s_add_u32 s0, s22, 0x1e000000
	v_writelane_b32 v254, s0, 8
	s_addc_u32 s0, s23, 0
	v_writelane_b32 v254, s0, 9
	s_lshl_b32 s0, s70, 12
	v_writelane_b32 v254, s0, 10
	s_lshl_b32 s0, s58, 12
	v_writelane_b32 v254, s0, 11
	s_add_u32 s0, s22, 4
	v_writelane_b32 v254, s0, 12
	s_addc_u32 s0, s23, 0
	v_writelane_b32 v254, s0, 13
	s_mul_hi_i32 s0, s6, 0xc0000
	v_writelane_b32 v254, s0, 14
	v_writelane_b32 v254, s6, 15
	s_mul_i32 s0, s6, 0xc0000
	v_writelane_b32 v254, s0, 16
	s_lshl_b32 s0, s70, 11
	s_ashr_i32 s35, s34, 31
	v_writelane_b32 v254, s0, 17
	s_lshl_b32 s0, s58, 11
	s_ashr_i32 s85, s84, 31
	v_writelane_b32 v254, s0, 18
	s_lshl_b64 s[0:1], s[34:35], 12
	s_ashr_i32 s17, s16, 31
	s_lshl_b64 s[90:91], s[84:85], 3
	v_writelane_b32 v254, s0, 19
	v_cmp_eq_u32_e64 s[6:7], 0, v4
	v_writelane_b32 v253, s18, 60
	v_writelane_b32 v254, s1, 20
	s_add_u32 s0, s22, 0x1a000400
	v_writelane_b32 v254, s0, 21
	s_addc_u32 s0, s23, 0
	v_writelane_b32 v254, s0, 22
	v_writelane_b32 v254, s16, 23
	s_add_i32 s0, s16, 0xfffff800
	s_lshl_b64 s[62:63], s[34:35], 11
	v_writelane_b32 v254, s17, 24
	v_writelane_b32 v254, s0, 25
	s_add_u32 s0, s22, 0xaa00100
	v_writelane_b32 v254, s0, 26
	s_addc_u32 s0, s23, 0
	v_writelane_b32 v254, s0, 27
	s_add_u32 s0, s22, 0xb600000
	v_writelane_b32 v254, s0, 28
	v_writelane_b32 v254, s20, 29
	s_addc_u32 s0, s23, 0
	v_mov_b64_e32 v[0:1], s[18:19]
	v_writelane_b32 v254, s21, 30
	v_writelane_b32 v254, s22, 31
	v_writelane_b32 v254, s23, 32
	v_writelane_b32 v254, s0, 33
	s_add_i32 s0, 0, 0x20000
	v_writelane_b32 v254, s0, 34
	v_writelane_b32 v254, s6, 35
	v_writelane_b32 v253, s19, 61
	v_writelane_b32 v253, s12, 62
	v_writelane_b32 v254, s7, 36
	v_cmp_gt_i64_e64 s[6:7], s[74:75], v[2:3]
	v_writelane_b32 v253, s13, 63
	v_mov_b64_e32 v[196:197], 0x6b
	v_writelane_b32 v254, s6, 37
	v_mov_b64_e32 v[198:199], 0x100
	v_mov_b64_e32 v[200:201], 0xff
	v_writelane_b32 v254, s7, 38
	v_writelane_b32 v254, s24, 39
	v_mov_b64_e32 v[202:203], 0x60
	v_mov_b64_e32 v[204:205], 0x5f
	v_writelane_b32 v254, s25, 40
	v_cmp_gt_i64_e64 s[6:7], s[24:25], v[0:1]
	v_mov_b64_e32 v[206:207], 0x400
	v_mov_b64_e32 v[208:209], 0x3ff
	v_writelane_b32 v254, s6, 41
	s_movk_i32 s95, 0x60
	s_movk_i32 s18, 0x300
	v_writelane_b32 v254, s7, 42
	v_writelane_b32 v254, s62, 43
	s_movk_i32 s73, 0xc00
	s_mov_b32 s61, 0xc000
	v_writelane_b32 v254, s63, 44
	v_writelane_b32 v254, s66, 45
	s_movk_i32 s92, 0x600
	s_movk_i32 s93, 0x1800
	v_writelane_b32 v254, s67, 46
	v_writelane_b32 v254, s70, 47
	v_writelane_b32 v254, s74, 48
	s_mov_b32 s85, 0x3c800000
	s_movk_i32 s5, 0x2000
	v_writelane_b32 v254, s75, 49
	v_writelane_b32 v254, s80, 50
	s_movk_i32 s1, 0x4000
	s_movk_i32 s88, 0x8ff
	v_writelane_b32 v254, s81, 51
	v_writelane_b32 v254, s34, 52
	s_mov_b32 s60, 0x39800000
	s_movk_i32 s3, 0x801
	v_writelane_b32 v254, s35, 53
	v_writelane_b32 v254, s71, 54
	v_writelane_b32 v254, s72, 55
	v_writelane_b32 v254, s90, 56
	s_mov_b64 s[38:39], -1
	s_mov_b64 s[56:57], 0x80
	s_mov_b32 s78, 0x3e16c740
	s_mov_b32 s10, 0
	s_brev_b32 s36, 1
	v_writelane_b32 v254, s91, 57
	s_branch .LBB0_2
